# EW phase: touch next unit's rows into L2 (one dword per lane, 256 units ahead) after the current unit's loads are consumed
# baseline (speedup 1.0000x reference)
; __device__ __forceinline__ unsigned pk2(float lo, float hi) { const f32x2_ v = {lo, hi}; const bf16x2_ r = __builtin_convertvector(v, bf16x2_); return __builtin_bit_cast(unsigned, r); }
; __device__ __forceinline__ float wave_sum(float v) { v = row16_sum(v); v += __shfl_xor(v, 16); v += __shfl_xor(v, 32); return v; }
; __device__ __forceinline__ float frsq(float x) { return __builtin_amdgcn_rsqf(x); }
; __device__ __forceinline__ float sigmoidf_(float x) { return frcp(1.f + fexp(-x)); }
; __device__ __forceinline__ float geluf_(float x) { const float u = 0.7978845608028654f * (x + 0.044715f * x * x * x); const float th = 1.0f - 2.0f * frcp(1.0f + fexp(2.0f * u)); return 0.5f * x * (1.f + th); }
; __device__ __forceinline__ v2u pack4(const f32x4 v) { v2u r; r.x = pk2(v[0], v[1]); r.y = pk2(v[2], v[3]); return r; }
; __device__ __forceinline__ f32x4 unpack4(const v2u w) { f32x4 r; r[0] = bflo(w.x); r[1] = bfhi(w.x); r[2] = bflo(w.y); r[3] = bfhi(w.y); return r; }
; __device__ __forceinline__ void ew_unit(const Frame& F, int l, int rg) {
;     ...
;     for (int j = 0; j < 2; ++j) { const bool isz = ((tid + 512 * j) & 63) < 32; v4u o; unsigned* oi = (unsigned*)&o; const unsigned* gi = (const unsigned*)&gr[j];
; #pragma unroll
;         for (int e = 0; e < 4; ++e) { const float a = bflo(gi[e]), bb = bfhi(gi[e]); const float sa = sigmoidf_(a), sb = sigmoidf_(bb); const float n0 = nwa[j][e >> 1][(e & 1) * 2], n1 = nwa[j][e >> 1][(e & 1) * 2 + 1];
;             oi[e] = isz ? pk2(a * sa * n0, bb * sb * n1) : pk2(sa * n0, sb * n1); }
;         *(v4u*)gp[j] = o; }
; #pragma unroll
;     for (int j = 0; j < 2; ++j) {
;         bf16_t* zr = F.Z + (size_t)(r0 + 2 * wave_ + j) * ZW + 4 * lane_;
;         f32x4 u = unpack4(ur[j]), v = unpack4(vr[j]); float ss = 0.f;
; #pragma unroll
;         for (int e = 0; e < 4; ++e) { u[e] = geluf_(u[e]); v[e] = geluf_(v[e]); ss += v[e] * v[e]; }
;         const float rs = frsq(wave_sum(ss) * (1.f / 256.f) + EPS);
;         *(v2u*)(zr + ZC_MU) = pack4(u); *(v2u*)(zr + ZC_MV) = pack4(v * rs * gnw);
.LBB0_765:
	s_or_b64 exec, exec, s[20:21]
	v_and_b32_e32 v22, 32, v54
	v_cmp_eq_u32_e32 vcc, 0, v22
	s_waitcnt vmcnt(6)
	v_lshlrev_b32_e32 v22, 16, v18
	v_and_b32_e32 v18, 0xffff0000, v18
	v_mul_f32_e32 v23, 0xbfb8aa3b, v22
	v_mul_f32_e32 v24, 0xbfb8aa3b, v18
	v_exp_f32_e32 v23, v23
	v_exp_f32_e32 v24, v24
	v_lshlrev_b32_e32 v0, 2, v55
	s_add_u32 s20, s16, s9
	v_add_f32_e32 v23, 1.0, v23
	v_add_f32_e32 v24, 1.0, v24
	v_rcp_f32_e32 v23, v23
	v_rcp_f32_e32 v24, v24
	s_addc_u32 s21, s17, s8
	v_mul_f32_e32 v22, v23, v22
	v_mul_f32_e32 v18, v24, v18
	v_cndmask_b32_e32 v18, v24, v18, vcc
	v_cndmask_b32_e32 v22, v23, v22, vcc
	v_mul_f32_e32 v22, v14, v22
	v_mul_f32_e32 v18, v15, v18
	v_cvt_pk_bf16_f32 v18, v22, v18
	v_lshlrev_b32_e32 v22, 16, v19
	v_and_b32_e32 v19, 0xffff0000, v19
	v_mul_f32_e32 v23, 0xbfb8aa3b, v22
	v_mul_f32_e32 v24, 0xbfb8aa3b, v19
	v_exp_f32_e32 v23, v23
	v_exp_f32_e32 v24, v24
	v_add_f32_e32 v23, 1.0, v23
	v_add_f32_e32 v24, 1.0, v24
	v_rcp_f32_e32 v23, v23
	v_rcp_f32_e32 v24, v24
	v_mul_f32_e32 v22, v23, v22
	v_mul_f32_e32 v19, v24, v19
	v_cndmask_b32_e32 v19, v24, v19, vcc
	v_cndmask_b32_e32 v22, v23, v22, vcc
	v_mul_f32_e32 v22, v16, v22
	v_mul_f32_e32 v19, v17, v19
	v_cvt_pk_bf16_f32 v19, v22, v19
	v_lshlrev_b32_e32 v22, 16, v20
	v_and_b32_e32 v20, 0xffff0000, v20
	v_mul_f32_e32 v23, 0xbfb8aa3b, v22
	v_mul_f32_e32 v24, 0xbfb8aa3b, v20
	v_exp_f32_e32 v23, v23
	v_exp_f32_e32 v24, v24
	v_add_f32_e32 v23, 1.0, v23
	v_add_f32_e32 v24, 1.0, v24
	v_rcp_f32_e32 v23, v23
	v_rcp_f32_e32 v24, v24
	v_mul_f32_e32 v22, v23, v22
	v_mul_f32_e32 v20, v24, v20
	v_cndmask_b32_e32 v20, v24, v20, vcc
	v_cndmask_b32_e32 v22, v23, v22, vcc
	v_mul_f32_e32 v22, v6, v22
	v_mul_f32_e32 v20, v7, v20
	v_cvt_pk_bf16_f32 v20, v22, v20
	v_lshlrev_b32_e32 v22, 16, v21
	v_and_b32_e32 v21, 0xffff0000, v21
	v_mul_f32_e32 v23, 0xbfb8aa3b, v22
	v_mul_f32_e32 v24, 0xbfb8aa3b, v21
	v_exp_f32_e32 v23, v23
	v_exp_f32_e32 v24, v24
	v_add_f32_e32 v23, 1.0, v23
	v_add_f32_e32 v24, 1.0, v24
	v_rcp_f32_e32 v23, v23
	v_rcp_f32_e32 v24, v24
	v_mul_f32_e32 v22, v23, v22
	v_mul_f32_e32 v21, v24, v21
	v_cndmask_b32_e32 v21, v24, v21, vcc
	v_cndmask_b32_e32 v22, v23, v22, vcc
	v_mul_f32_e32 v22, v8, v22
	v_mul_f32_e32 v21, v9, v21
	v_cvt_pk_bf16_f32 v21, v22, v21
	global_store_dwordx4 v[48:49], v[18:21], off
	s_waitcnt vmcnt(6)
	s_nop 0
	v_lshlrev_b32_e32 v18, 16, v10
	v_and_b32_e32 v10, 0xffff0000, v10
	v_mul_f32_e32 v20, 0xbfb8aa3b, v10
	v_mul_f32_e32 v19, 0xbfb8aa3b, v18
	v_exp_f32_e32 v20, v20
	v_exp_f32_e32 v19, v19
	v_add_f32_e32 v20, 1.0, v20
	v_add_f32_e32 v19, 1.0, v19
	v_rcp_f32_e32 v20, v20
	v_rcp_f32_e32 v19, v19
	v_mul_f32_e32 v10, v20, v10
	v_mul_f32_e32 v18, v19, v18
	v_cndmask_b32_e32 v10, v20, v10, vcc
	v_cndmask_b32_e32 v18, v19, v18, vcc
	v_mul_f32_e32 v10, v15, v10
	v_lshlrev_b32_e32 v15, 16, v11
	v_mul_f32_e32 v14, v14, v18
	v_and_b32_e32 v11, 0xffff0000, v11
	v_mul_f32_e32 v18, 0xbfb8aa3b, v15
	v_exp_f32_e32 v18, v18
	v_mul_f32_e32 v19, 0xbfb8aa3b, v11
	v_exp_f32_e32 v19, v19
	v_add_f32_e32 v18, 1.0, v18
	v_rcp_f32_e32 v18, v18
	v_add_f32_e32 v19, 1.0, v19
	v_rcp_f32_e32 v19, v19
	v_mul_f32_e32 v15, v18, v15
	v_cndmask_b32_e32 v15, v18, v15, vcc
	v_mul_f32_e32 v11, v19, v11
	v_cndmask_b32_e32 v11, v19, v11, vcc
	v_mul_f32_e32 v15, v16, v15
	v_lshlrev_b32_e32 v16, 16, v12
	v_and_b32_e32 v12, 0xffff0000, v12
	v_mul_f32_e32 v11, v17, v11
	v_mul_f32_e32 v17, 0xbfb8aa3b, v16
	v_mul_f32_e32 v18, 0xbfb8aa3b, v12
	v_exp_f32_e32 v17, v17
	v_exp_f32_e32 v18, v18
	v_add_f32_e32 v17, 1.0, v17
	v_add_f32_e32 v18, 1.0, v18
	v_rcp_f32_e32 v17, v17
	v_rcp_f32_e32 v18, v18
	v_mul_f32_e32 v16, v17, v16
	v_mul_f32_e32 v12, v18, v12
	v_cndmask_b32_e32 v12, v18, v12, vcc
	v_cndmask_b32_e32 v16, v17, v16, vcc
	v_mul_f32_e32 v16, v6, v16
	v_mul_f32_e32 v12, v7, v12
	v_lshlrev_b32_e32 v6, 16, v13
	v_and_b32_e32 v7, 0xffff0000, v13
	v_mul_f32_e32 v13, 0xbfb8aa3b, v6
	v_mul_f32_e32 v17, 0xbfb8aa3b, v7
	v_exp_f32_e32 v13, v13
	v_exp_f32_e32 v17, v17
	v_add_f32_e32 v13, 1.0, v13
	v_add_f32_e32 v17, 1.0, v17
	v_rcp_f32_e32 v13, v13
	v_rcp_f32_e32 v17, v17
	v_mul_f32_e32 v6, v13, v6
	v_mul_f32_e32 v7, v17, v7
	v_cndmask_b32_e32 v7, v17, v7, vcc
	v_cndmask_b32_e32 v6, v13, v6, vcc
	v_mul_f32_e32 v13, v8, v6
	v_mul_f32_e32 v9, v9, v7
	v_cvt_pk_bf16_f32 v6, v14, v10
	v_cvt_pk_bf16_f32 v7, v15, v11
	v_cvt_pk_bf16_f32 v8, v16, v12
	v_cvt_pk_bf16_f32 v9, v13, v9
	global_store_dwordx4 v[46:47], v[6:9], off
	s_waitcnt vmcnt(6)
	v_and_b32_e32 v15, 0xffff0000, v45
	v_mov_b32_e32 v18, v15
	v_and_b32_e32 v7, 64, v232
	v_xor_b32_e32 v6, 16, v232
	v_add_u32_e32 v7, 64, v7
	v_cmp_lt_i32_e32 vcc, v6, v7
	s_nop 1
	v_cndmask_b32_e32 v6, v232, v6, vcc
	v_lshlrev_b32_e32 v9, 2, v6
	v_xor_b32_e32 v6, 32, v232
	v_cmp_lt_i32_e32 vcc, v6, v7
	v_and_b32_e32 v7, 0xffff0000, v44
	v_mov_b32_e32 v12, v7
	v_cndmask_b32_e32 v6, v232, v6, vcc
	v_lshlrev_b32_e32 v8, 2, v6
	v_lshlrev_b32_e32 v6, 16, v44
	v_mul_f32_e32 v10, 0x3d372713, v6
	v_mul_f32_e32 v10, v10, v6
	v_mov_b32_e32 v11, v6
	v_fmac_f32_e32 v11, v10, v11
	v_mul_f32_e32 v10, 0x3f4c422a, v11
	v_mul_f32_e32 v11, 0x3d372713, v7
	v_mul_f32_e32 v11, v11, v7
	v_fmac_f32_e32 v12, v11, v12
	v_mul_f32_e32 v11, 0x3f4c422a, v12
	v_add_f32_e32 v10, v10, v10
	v_add_f32_e32 v11, v11, v11
	v_mul_f32_e32 v10, 0x3fb8aa3b, v10
	v_mul_f32_e32 v11, 0x3fb8aa3b, v11
	v_exp_f32_e32 v10, v10
	v_exp_f32_e32 v11, v11
	v_pk_mul_f32 v[6:7], v[6:7], 0.5 op_sel_hi:[1,0]
	v_add_f32_e32 v10, 1.0, v10
	v_add_f32_e32 v11, 1.0, v11
	v_rcp_f32_e32 v10, v10
	v_rcp_f32_e32 v11, v11
	s_nop 0
	v_pk_fma_f32 v[10:11], v[10:11], 2.0, 1.0 op_sel_hi:[1,0,0] neg_lo:[1,0,0] neg_hi:[1,0,0]
	s_nop 0
	v_pk_add_f32 v[10:11], v[10:11], 1.0 op_sel_hi:[1,0]
	s_nop 0
	v_pk_mul_f32 v[6:7], v[6:7], v[10:11]
	s_waitcnt vmcnt(5)
; __device__ __forceinline__ float wave_sum(float v) { v = row16_sum(v); v += __shfl_xor(v, 16); v += __shfl_xor(v, 32); return v; }
; __device__ __forceinline__ float frsq(float x) { return __builtin_amdgcn_rsqf(x); }
; __device__ __forceinline__ float geluf_(float x) { const float u = 0.7978845608028654f * (x + 0.044715f * x * x * x); const float th = 1.0f - 2.0f * frcp(1.0f + fexp(2.0f * u)); return 0.5f * x * (1.f + th); }
; __device__ __forceinline__ v2u pack4(const f32x4 v) { v2u r; r.x = pk2(v[0], v[1]); r.y = pk2(v[2], v[3]); return r; }
; __device__ __forceinline__ f32x4 unpack4(const v2u w) { f32x4 r; r[0] = bflo(w.x); r[1] = bfhi(w.x); r[2] = bflo(w.y); r[3] = bfhi(w.y); return r; }
; __device__ __forceinline__ void ew_unit(const Frame& F, int l, int rg) {
;     ...
;     for (int j = 0; j < 2; ++j) {
;         bf16_t* zr = F.Z + (size_t)(r0 + 2 * wave_ + j) * ZW + 4 * lane_;
;         f32x4 u = unpack4(ur[j]), v = unpack4(vr[j]); float ss = 0.f;
; #pragma unroll
;         for (int e = 0; e < 4; ++e) { u[e] = geluf_(u[e]); v[e] = geluf_(v[e]); ss += v[e] * v[e]; }
;         const float rs = frsq(wave_sum(ss) * (1.f / 256.f) + EPS);
;         *(v2u*)(zr + ZC_MU) = pack4(u); *(v2u*)(zr + ZC_MV) = pack4(v * rs * gnw);
	v_lshlrev_b32_e32 v10, 16, v42
	v_mul_f32_e32 v12, 0x3d372713, v10
	v_mul_f32_e32 v12, v12, v10
	v_mov_b32_e32 v13, v10
	v_and_b32_e32 v11, 0xffff0000, v42
	v_fmac_f32_e32 v13, v12, v13
	v_mul_f32_e32 v12, 0x3f4c422a, v13
	v_mul_f32_e32 v13, 0x3d372713, v11
	v_mul_f32_e32 v13, v13, v11
	v_mov_b32_e32 v14, v11
	v_fmac_f32_e32 v14, v13, v14
	v_mul_f32_e32 v13, 0x3f4c422a, v14
	v_lshlrev_b32_e32 v14, 16, v45
	v_mul_f32_e32 v16, 0x3d372713, v14
	v_mul_f32_e32 v16, v16, v14
	v_mov_b32_e32 v17, v14
	v_fmac_f32_e32 v17, v16, v17
	v_mul_f32_e32 v16, 0x3f4c422a, v17
	v_mul_f32_e32 v17, 0x3d372713, v15
	v_mul_f32_e32 v17, v17, v15
	v_fmac_f32_e32 v18, v17, v18
	v_mul_f32_e32 v17, 0x3f4c422a, v18
	v_add_f32_e32 v16, v16, v16
	v_add_f32_e32 v17, v17, v17
	v_mul_f32_e32 v16, 0x3fb8aa3b, v16
	v_mul_f32_e32 v17, 0x3fb8aa3b, v17
	v_exp_f32_e32 v16, v16
	v_exp_f32_e32 v17, v17
	v_pk_mul_f32 v[14:15], v[14:15], 0.5 op_sel_hi:[1,0]
	v_add_f32_e32 v12, v12, v12
	v_add_f32_e32 v16, 1.0, v16
	v_add_f32_e32 v17, 1.0, v17
	v_rcp_f32_e32 v16, v16
	v_rcp_f32_e32 v17, v17
	v_add_f32_e32 v13, v13, v13
	v_mul_f32_e32 v12, 0x3fb8aa3b, v12
	v_mul_f32_e32 v13, 0x3fb8aa3b, v13
	v_pk_fma_f32 v[16:17], v[16:17], 2.0, 1.0 op_sel_hi:[1,0,0] neg_lo:[1,0,0] neg_hi:[1,0,0]
	v_exp_f32_e32 v12, v12
	v_pk_add_f32 v[16:17], v[16:17], 1.0 op_sel_hi:[1,0]
	v_exp_f32_e32 v13, v13
	v_pk_mul_f32 v[14:15], v[14:15], v[16:17]
	v_lshlrev_b32_e32 v16, 16, v43
	v_mul_f32_e32 v18, 0x3d372713, v16
	v_mul_f32_e32 v18, v18, v16
	v_mov_b32_e32 v19, v16
	v_and_b32_e32 v17, 0xffff0000, v43
	v_fmac_f32_e32 v19, v18, v19
	v_mul_f32_e32 v18, 0x3f4c422a, v19
	v_mul_f32_e32 v19, 0x3d372713, v17
	v_mul_f32_e32 v19, v19, v17
	v_mov_b32_e32 v20, v17
	v_fmac_f32_e32 v20, v19, v20
	v_mul_f32_e32 v19, 0x3f4c422a, v20
	v_add_f32_e32 v18, v18, v18
	v_add_f32_e32 v19, v19, v19
	v_mul_f32_e32 v18, 0x3fb8aa3b, v18
	v_mul_f32_e32 v19, 0x3fb8aa3b, v19
	v_exp_f32_e32 v18, v18
	v_exp_f32_e32 v19, v19
	v_add_f32_e32 v12, 1.0, v12
	v_add_f32_e32 v13, 1.0, v13
	v_rcp_f32_e32 v12, v12
	v_rcp_f32_e32 v13, v13
	v_add_f32_e32 v18, 1.0, v18
	v_add_f32_e32 v19, 1.0, v19
	v_rcp_f32_e32 v18, v18
	v_rcp_f32_e32 v19, v19
	v_pk_fma_f32 v[12:13], v[12:13], 2.0, 1.0 op_sel_hi:[1,0,0] neg_lo:[1,0,0] neg_hi:[1,0,0]
	v_pk_mul_f32 v[10:11], v[10:11], 0.5 op_sel_hi:[1,0]
	v_pk_add_f32 v[12:13], v[12:13], 1.0 op_sel_hi:[1,0]
	v_pk_fma_f32 v[18:19], v[18:19], 2.0, 1.0 op_sel_hi:[1,0,0] neg_lo:[1,0,0] neg_hi:[1,0,0]
	v_pk_mul_f32 v[10:11], v[10:11], v[12:13]
	v_pk_mul_f32 v[16:17], v[16:17], 0.5 op_sel_hi:[1,0]
	v_pk_add_f32 v[18:19], v[18:19], 1.0 op_sel_hi:[1,0]
	v_pk_mul_f32 v[12:13], v[10:11], v[10:11]
	v_pk_mul_f32 v[16:17], v[16:17], v[18:19]
	v_add_f32_e32 v12, v12, v13
	v_pk_mul_f32 v[18:19], v[16:17], v[16:17]
	v_lshlrev_b32_e32 v20, 1, v0
	v_add_f32_e32 v12, v18, v12
	v_add_f32_e32 v12, v19, v12
	v_cvt_pk_bf16_f32 v6, v6, v7
	v_cvt_pk_bf16_f32 v7, v14, v15
	v_add_f32_dpp v0, v12, v12 quad_perm:[1,0,3,2] row_mask:0xf bank_mask:0xf bound_ctrl:1
	global_store_dwordx2 v20, v[6:7], s[20:21] offset:3072
	s_waitcnt vmcnt(5)
	v_lshlrev_b32_e32 v14, 16, v41
	v_add_f32_dpp v0, v0, v0 quad_perm:[2,3,0,1] row_mask:0xf bank_mask:0xf bound_ctrl:1
	v_and_b32_e32 v15, 0xffff0000, v41
	s_nop 0
	v_add_f32_dpp v0, v0, v0 row_half_mirror row_mask:0xf bank_mask:0xf bound_ctrl:1
	s_nop 1
	v_add_f32_dpp v0, v0, v0 row_mirror row_mask:0xf bank_mask:0xf bound_ctrl:1
	ds_bpermute_b32 v12, v9, v0
	s_waitcnt lgkmcnt(0)
	v_add_f32_e32 v0, v0, v12
	ds_bpermute_b32 v12, v8, v0
	s_waitcnt lgkmcnt(0)
	v_add_f32_e32 v0, v0, v12
	v_fmamk_f32 v0, v0, 0x3b800000, v231
	v_rsq_f32_e32 v0, v0
	s_nop 0
	v_pk_mul_f32 v[6:7], v[10:11], v[0:1] op_sel_hi:[1,0]
	v_pk_mul_f32 v[10:11], v[16:17], v[0:1] op_sel_hi:[1,0]
	s_waitcnt vmcnt(3)
	v_pk_mul_f32 v[6:7], v[2:3], v[6:7]
	v_pk_mul_f32 v[10:11], v[4:5], v[10:11]
	v_cvt_pk_bf16_f32 v6, v6, v7
	v_cvt_pk_bf16_f32 v7, v10, v11
	global_store_dwordx2 v20, v[6:7], s[20:21] offset:3584
	s_cmpk_gt_i32 s3, 0x37f
	s_cbranch_scc1 .Lew_nopf
	global_load_dword v140, v[130:131], off
	global_load_dword v141, v[132:133], off
	global_load_dword v142, v[134:135], off offset:3072
	global_load_dword v143, v[134:135], off offset:3584
	global_load_dword v144, v[136:137], off offset:3072
	global_load_dword v145, v[136:137], off offset:3584
	global_load_dword v146, v[138:139], off offset:2048
	global_load_dword v147, v[138:139], off offset:2112
; __device__ __forceinline__ float wave_sum(float v) { v = row16_sum(v); v += __shfl_xor(v, 16); v += __shfl_xor(v, 32); return v; }
; __device__ __forceinline__ float frsq(float x) { return __builtin_amdgcn_rsqf(x); }
; __device__ __forceinline__ float geluf_(float x) { const float u = 0.7978845608028654f * (x + 0.044715f * x * x * x); const float th = 1.0f - 2.0f * frcp(1.0f + fexp(2.0f * u)); return 0.5f * x * (1.f + th); }
; __device__ __forceinline__ v2u pack4(const f32x4 v) { v2u r; r.x = pk2(v[0], v[1]); r.y = pk2(v[2], v[3]); return r; }
; __device__ __forceinline__ f32x4 unpack4(const v2u w) { f32x4 r; r[0] = bflo(w.x); r[1] = bfhi(w.x); r[2] = bflo(w.y); r[3] = bfhi(w.y); return r; }
; __device__ __forceinline__ void ew_unit(const Frame& F, int l, int rg) {
;     ...
;     for (int j = 0; j < 2; ++j) {
;         bf16_t* zr = F.Z + (size_t)(r0 + 2 * wave_ + j) * ZW + 4 * lane_;
;         f32x4 u = unpack4(ur[j]), v = unpack4(vr[j]); float ss = 0.f;
; #pragma unroll
;         for (int e = 0; e < 4; ++e) { u[e] = geluf_(u[e]); v[e] = geluf_(v[e]); ss += v[e] * v[e]; }
;         const float rs = frsq(wave_sum(ss) * (1.f / 256.f) + EPS);
;         *(v2u*)(zr + ZC_MU) = pack4(u); *(v2u*)(zr + ZC_MV) = pack4(v * rs * gnw);
.Lew_nopf:
	v_lshlrev_b32_e32 v6, 16, v40
	v_mul_f32_e32 v0, 0x3d372713, v6
	v_mul_f32_e32 v0, v0, v6
	v_mov_b32_e32 v10, v6
	v_fmac_f32_e32 v10, v0, v10
	v_mul_f32_e32 v0, 0x3f4c422a, v10
	v_add_f32_e32 v0, v0, v0
	v_mul_f32_e32 v0, 0x3fb8aa3b, v0
	v_exp_f32_e32 v0, v0
	v_and_b32_e32 v7, 0xffff0000, v40
	v_mov_b32_e32 v11, v7
	v_mov_b32_e32 v16, v14
	v_add_f32_e32 v0, 1.0, v0
	v_rcp_f32_e32 v10, v0
	v_mul_f32_e32 v0, 0x3d372713, v7
	v_mul_f32_e32 v0, v0, v7
	v_fmac_f32_e32 v11, v0, v11
	v_mul_f32_e32 v0, 0x3f4c422a, v11
	v_add_f32_e32 v0, v0, v0
	v_mul_f32_e32 v0, 0x3fb8aa3b, v0
	v_exp_f32_e32 v0, v0
	v_pk_mul_f32 v[6:7], v[6:7], 0.5 op_sel_hi:[1,0]
	v_mov_b32_e32 v17, v15
	s_add_u32 s20, s16, s7
	v_add_f32_e32 v0, 1.0, v0
	v_rcp_f32_e32 v11, v0
	s_addc_u32 s21, s17, s6
	v_pk_fma_f32 v[10:11], v[10:11], 2.0, 1.0 op_sel_hi:[1,0,0] neg_lo:[1,0,0] neg_hi:[1,0,0]
	s_nop 0
	v_pk_add_f32 v[10:11], v[10:11], 1.0 op_sel_hi:[1,0]
	s_nop 0
	v_pk_mul_f32 v[6:7], v[6:7], v[10:11]
	v_lshlrev_b32_e32 v10, 16, v38
	v_mul_f32_e32 v0, 0x3d372713, v10
	v_mul_f32_e32 v0, v0, v10
	v_mov_b32_e32 v12, v10
	v_fmac_f32_e32 v12, v0, v12
	v_mul_f32_e32 v0, 0x3f4c422a, v12
	v_add_f32_e32 v0, v0, v0
	v_mul_f32_e32 v0, 0x3fb8aa3b, v0
	v_exp_f32_e32 v0, v0
	v_and_b32_e32 v11, 0xffff0000, v38
	v_mov_b32_e32 v13, v11
	v_cvt_pk_bf16_f32 v6, v6, v7
	v_add_f32_e32 v0, 1.0, v0
	v_rcp_f32_e32 v12, v0
	v_mul_f32_e32 v0, 0x3d372713, v11
	v_mul_f32_e32 v0, v0, v11
	v_fmac_f32_e32 v13, v0, v13
	v_mul_f32_e32 v0, 0x3f4c422a, v13
	v_add_f32_e32 v0, v0, v0
	v_mul_f32_e32 v0, 0x3fb8aa3b, v0
	v_exp_f32_e32 v0, v0
	v_pk_mul_f32 v[10:11], v[10:11], 0.5 op_sel_hi:[1,0]
	v_add_f32_e32 v0, 1.0, v0
	v_rcp_f32_e32 v13, v0
	v_mul_f32_e32 v0, 0x3d372713, v14
	v_mul_f32_e32 v0, v0, v14
	v_fmac_f32_e32 v16, v0, v16
	v_mul_f32_e32 v0, 0x3f4c422a, v16
	v_add_f32_e32 v0, v0, v0
	v_mul_f32_e32 v0, 0x3fb8aa3b, v0
	v_exp_f32_e32 v0, v0
	v_pk_fma_f32 v[12:13], v[12:13], 2.0, 1.0 op_sel_hi:[1,0,0] neg_lo:[1,0,0] neg_hi:[1,0,0]
	v_add_f32_e32 v0, 1.0, v0
	v_rcp_f32_e32 v16, v0
	v_mul_f32_e32 v0, 0x3d372713, v15
	v_mul_f32_e32 v0, v0, v15
	v_fmac_f32_e32 v17, v0, v17
	v_mul_f32_e32 v0, 0x3f4c422a, v17
	v_add_f32_e32 v0, v0, v0
	v_mul_f32_e32 v0, 0x3fb8aa3b, v0
	v_exp_f32_e32 v0, v0
	v_pk_mul_f32 v[14:15], v[14:15], 0.5 op_sel_hi:[1,0]
	v_pk_add_f32 v[12:13], v[12:13], 1.0 op_sel_hi:[1,0]
	v_add_f32_e32 v0, 1.0, v0
	v_rcp_f32_e32 v17, v0
	v_pk_mul_f32 v[10:11], v[10:11], v[12:13]
	v_pk_fma_f32 v[16:17], v[16:17], 2.0, 1.0 op_sel_hi:[1,0,0] neg_lo:[1,0,0] neg_hi:[1,0,0]
	s_nop 0
	v_pk_add_f32 v[16:17], v[16:17], 1.0 op_sel_hi:[1,0]
	v_pk_mul_f32 v[12:13], v[10:11], v[10:11]
	v_pk_mul_f32 v[14:15], v[14:15], v[16:17]
	v_lshlrev_b32_e32 v16, 16, v39
	v_mul_f32_e32 v0, 0x3d372713, v16
	v_mul_f32_e32 v0, v0, v16
	v_mov_b32_e32 v18, v16
	v_fmac_f32_e32 v18, v0, v18
	v_mul_f32_e32 v0, 0x3f4c422a, v18
	v_add_f32_e32 v0, v0, v0
	v_mul_f32_e32 v0, 0x3fb8aa3b, v0
	v_exp_f32_e32 v0, v0
	v_and_b32_e32 v17, 0xffff0000, v39
	v_mov_b32_e32 v19, v17
	v_cvt_pk_bf16_f32 v7, v14, v15
	v_add_f32_e32 v0, 1.0, v0
	v_rcp_f32_e32 v18, v0
	v_mul_f32_e32 v0, 0x3d372713, v17
	v_mul_f32_e32 v0, v0, v17
	v_fmac_f32_e32 v19, v0, v19
	v_mul_f32_e32 v0, 0x3f4c422a, v19
	v_add_f32_e32 v0, v0, v0
	v_mul_f32_e32 v0, 0x3fb8aa3b, v0
	v_exp_f32_e32 v0, v0
	v_pk_mul_f32 v[16:17], v[16:17], 0.5 op_sel_hi:[1,0]
	global_store_dwordx2 v20, v[6:7], s[20:21] offset:3072
	v_add_f32_e32 v0, 1.0, v0
	v_rcp_f32_e32 v19, v0
	v_add_f32_e32 v0, v12, v13
	v_pk_fma_f32 v[18:19], v[18:19], 2.0, 1.0 op_sel_hi:[1,0,0] neg_lo:[1,0,0] neg_hi:[1,0,0]
	s_nop 0
	v_pk_add_f32 v[18:19], v[18:19], 1.0 op_sel_hi:[1,0]
	s_nop 0
	v_pk_mul_f32 v[16:17], v[16:17], v[18:19]
	s_nop 0
	v_pk_mul_f32 v[18:19], v[16:17], v[16:17]
	s_nop 0
	v_add_f32_e32 v0, v18, v0
	v_add_f32_e32 v0, v19, v0
	s_nop 1
	v_add_f32_dpp v0, v0, v0 quad_perm:[1,0,3,2] row_mask:0xf bank_mask:0xf bound_ctrl:1
	s_nop 1
	v_add_f32_dpp v0, v0, v0 quad_perm:[2,3,0,1] row_mask:0xf bank_mask:0xf bound_ctrl:1
	s_nop 1
	v_add_f32_dpp v0, v0, v0 row_half_mirror row_mask:0xf bank_mask:0xf bound_ctrl:1
	s_nop 1
	v_add_f32_dpp v0, v0, v0 row_mirror row_mask:0xf bank_mask:0xf bound_ctrl:1
	ds_bpermute_b32 v9, v9, v0
	s_waitcnt lgkmcnt(0)
	v_add_f32_e32 v0, v0, v9
	ds_bpermute_b32 v8, v8, v0
	s_waitcnt lgkmcnt(0)
	v_add_f32_e32 v0, v0, v8
	v_fmamk_f32 v0, v0, 0x3b800000, v231
	v_rsq_f32_e32 v0, v0
	s_nop 0
	v_pk_mul_f32 v[6:7], v[10:11], v[0:1] op_sel_hi:[1,0]
	v_pk_mul_f32 v[8:9], v[16:17], v[0:1] op_sel_hi:[1,0]
	v_pk_mul_f32 v[2:3], v[2:3], v[6:7]
	v_pk_mul_f32 v[4:5], v[4:5], v[8:9]
	v_cvt_pk_bf16_f32 v2, v2, v3
	v_cvt_pk_bf16_f32 v3, v4, v5
	global_store_dwordx2 v20, v[2:3], s[20:21] offset:3584

; #define LAS __attribute__((address_space(3)))
; __device__ __forceinline__ void ew_unit(const Frame& F, int l, int rg) {
;     const int r0 = rg * 16;
;     const int t_o = F.wave * 64 + fresh_lane();
;     const int tid = t_o, lane_ = t_o & 63, wave_ = __builtin_amdgcn_readfirstlane(t_o >> 6);
;     const int ti = tid < 384 ? tid : 383;
;     const int rr_ = ti / 24, rem_ = ti % 24, hd = rem_ >> 2, g = rem_ & 3, row = r0 + rr_;
;     bf16_t* p = F.Z + (size_t)row * ZW + (hd < 4 ? ZC_SQ + hd * 64 : ZC_SK + (hd - 4) * 64) + g * 8;
;     const v4u va = *(const v4u*)p, vb = *(const v4u*)(p + 32);
;     v4u gr[2]; bf16_t* gp[2]; f32x4 nwa[2][2];
; #pragma unroll
;     for (int j = 0; j < 2; ++j) { const int gg = tid + 512 * j, rr = gg >> 6, seg = gg & 63; gp[j] = F.Z + (size_t)(r0 + rr) * ZW + (seg < 32 ? ZC_GZ + seg * 8 : ZC_LO + (seg - 32) * 8); gr[j] = *(const v4u*)gp[j];
;         const float* nwp = seg < 32 ? F.gdn_norm_w + l * 64 + (seg & 7) * 8 : F.mlstm_norm_w + l * 256 + (seg - 32) * 8; nwa[j][0] = *(const f32x4*)nwp; nwa[j][1] = *(const f32x4*)(nwp + 4); }
;     v2u ur[2], vr[2];
; #pragma unroll
;     for (int j = 0; j < 2; ++j) { const bf16_t* zr = F.Z + (size_t)(r0 + 2 * wave_ + j) * ZW + 4 * lane_; ur[j] = *(const v2u*)(zr + ZC_MU); vr[j] = *(const v2u*)(zr + ZC_MV); }
;     const f32x4 gnw = *(const f32x4*)(F.gmlp_norm_w + l * 256 + 4 * lane_);
;     if (tid < 384) {
;         const unsigned* ai = (const unsigned*)&va; const unsigned* bi = (const unsigned*)&vb;
;         if (row < MLAT) {
;             const int t = row & (SEQ - 1);
;             const LAS float* tp = (const LAS float*)(F.lds + 8192) + ((g < 2 ? (t >> 6) : (t & 63)) * 16 + (g & 1) * 8) * 2;
;             const f32x4 c0 = *(const LAS f32x4*)tp, c1 = *(const LAS f32x4*)(tp + 4), c2 = *(const LAS f32x4*)(tp + 8), c3 = *(const LAS f32x4*)(tp + 12);
;             const float csn[16] = {c0[0], c0[1], c0[2], c0[3], c1[0], c1[1], c1[2], c1[3], c2[0], c2[1], c2[2], c2[3], c3[0], c3[1], c3[2], c3[3]};
;             const float sc = hd < 4 ? 0.125f : 1.0f;
;             v4u oa, ob; unsigned* oai = (unsigned*)&oa; unsigned* obi = (unsigned*)&ob;
; #pragma unroll
;             for (int e2 = 0; e2 < 4; ++e2) {
;                 float ra[2], rb[2];
; #pragma unroll
;                 for (int k = 0; k < 2; ++k) { const int e = 2 * e2 + k;
.LBB0_809:
	s_and_b64 vcc, exec, s[12:13]
	s_cbranch_vccz .LBB0_766
	v_mbcnt_lo_u32_b32 v54, -1, 0
	v_mbcnt_hi_u32_b32 v54, -1, v54
	v_mov_b32_e32 v0, 0xa00
	v_and_b32_e32 v55, 63, v54
	v_cmp_gt_u32_e32 vcc, 32, v55
	v_mov_b32_e32 v3, 0x300
	v_lshlrev_b32_e32 v2, 3, v55
	v_cndmask_b32_e32 v0, v0, v3, vcc
	v_or_b32_e32 v0, v0, v2
	v_lshlrev_b32_e32 v0, 1, v0
	v_lshl_add_u64 v[4:5], s[16:17], 0, v[0:1]
	v_lshlrev_b32_e32 v0, 5, v55
	v_lshl_add_u64 v[6:7], s[0:1], 0, v[0:1]
	v_lshlrev_b32_e32 v0, 5, v54
	v_add_u32_e32 v22, s64, v54
	v_and_b32_e32 v0, 0xe0, v0
	s_lshl_b32 s12, s3, 4
	s_movk_i32 s6, 0xfc00
	v_lshl_add_u64 v[8:9], s[4:5], 0, v[0:1]
	v_ashrrev_i32_e32 v0, 6, v22
	s_mov_b32 s7, -1
	v_add_u32_e32 v0, s12, v0
	v_lshl_add_u64 v[6:7], v[6:7], 0, s[6:7]
	v_mad_i64_i32 v[48:49], s[6:7], v0, s66, v[4:5]
	v_add_u32_e32 v0, 0x200, v22
	v_ashrrev_i32_e32 v0, 6, v0
	v_add_u32_e32 v0, s12, v0
	v_readfirstlane_b32 s8, v22
	v_mad_i64_i32 v[46:47], s[6:7], v0, s66, v[4:5]
	s_ashr_i32 s6, s8, 5
	v_mov_b32_e32 v3, v1
	s_and_b32 s6, s6, -2
	s_add_i32 s9, s6, s12
	v_lshl_add_u64 v[2:3], s[16:17], 0, v[2:3]
	v_mov_b32_e32 v0, 0x1a00
	v_cndmask_b32_e32 v11, v7, v9, vcc
	v_cndmask_b32_e32 v10, v6, v8, vcc
	v_mad_i64_i32 v[4:5], s[6:7], s9, v0, v[2:3]
	s_or_b32 s13, s9, 1
	global_load_dwordx4 v[6:9], v[10:11], off offset:16
	global_load_dwordx4 v[14:17], v[10:11], off
	global_load_dwordx4 v[18:21], v[48:49], off
	s_nop 0
	global_load_dwordx4 v[10:13], v[46:47], off
	v_mad_i64_i32 v[2:3], s[6:7], s13, v0, v[2:3]
	global_load_dwordx2 v[44:45], v[4:5], off offset:3072
	global_load_dwordx2 v[42:43], v[4:5], off offset:3584
	global_load_dwordx2 v[40:41], v[2:3], off offset:3072
	global_load_dwordx2 v[38:39], v[2:3], off offset:3584
	s_mov_b32 s98, 0x1a00000
	s_mov_b32 s99, 0
	v_lshl_add_u64 v[130:131], v[48:49], 0, s[98:99]
	v_lshl_add_u64 v[132:133], v[46:47], 0, s[98:99]
	v_lshl_add_u64 v[134:135], v[4:5], 0, s[98:99]
	v_lshl_add_u64 v[136:137], v[2:3], 0, s[98:99]
	v_mov_b32_e32 v138, v130
	v_mov_b32_e32 v139, v131
	v_lshlrev_b32_e32 v0, 4, v55
	global_load_dwordx4 v[2:5], v0, s[10:11]
	s_movk_i32 s6, 0x180
	v_cmp_gt_i32_e32 vcc, s6, v22
	s_mul_hi_i32 s8, s9, 0x1a00
	s_mulk_i32 s9, 0x1a00
	s_mul_hi_i32 s6, s13, 0x1a00
	s_mul_i32 s7, s13, 0x1a00
	s_and_saveexec_b64 s[20:21], vcc
	s_cbranch_execz .LBB0_765
	v_mov_b32_e32 v0, 0x17f
	v_cndmask_b32_e32 v0, v0, v22, vcc
	s_mov_b32 s13, 0x2aaaaaab
	v_mul_hi_i32 v22, v0, s13
	v_lshrrev_b32_e32 v23, 31, v22
	v_ashrrev_i32_e32 v22, 2, v22
	v_add_u32_e32 v22, v22, v23
	v_mul_lo_u32 v23, v22, 24
	v_sub_u32_e32 v56, v0, v23
	v_ashrrev_i32_e32 v26, 2, v56
	v_add_u32_e32 v58, s12, v22
	v_mov_b64_e32 v[22:23], s[16:17]
	v_lshlrev_b32_e32 v24, 6, v26
	v_and_b32_e32 v57, 3, v56
	v_mad_i64_i32 v[22:23], s[12:13], v58, s66, v[22:23]
	v_ashrrev_i32_e32 v25, 31, v24
	v_lshl_add_u64 v[22:23], v[24:25], 1, v[22:23]
	v_lshlrev_b32_e32 v0, 4, v57
	v_lshl_add_u64 v[50:51], v[22:23], 0, v[0:1]
	global_load_dwordx4 v[34:37], v[50:51], off offset:2048
	global_load_dwordx4 v[30:33], v[50:51], off offset:2112
	v_lshl_add_u64 v[138:139], v[50:51], 0, s[98:99]
	s_movk_i32 s12, 0x3fff
	v_cmp_gt_i32_e32 vcc, 4, v26
	v_cmp_lt_i32_e64 s[38:39], s12, v58
	s_mov_b64 s[22:23], 0
	s_and_saveexec_b64 s[12:13], s[38:39]
	s_xor_b64 s[24:25], exec, s[12:13]
	s_cbranch_execz .LBB0_816
	s_and_saveexec_b64 s[12:13], vcc
	s_xor_b64 s[26:27], exec, s[12:13]
	s_cbranch_execz .LBB0_814
	s_mov_b32 s12, 0x3e000000
	s_waitcnt vmcnt(0)
	v_lshlrev_b32_e32 v24, 16, v30
	v_and_b32_e32 v25, 0xffff0000, v30
	v_pk_mul_f32 v[24:25], v[24:25], s[12:13] op_sel_hi:[1,0]
	v_lshlrev_b32_e32 v22, 16, v34
	v_and_b32_e32 v23, 0xffff0000, v34
	v_cvt_pk_bf16_f32 v26, v24, v25
	v_lshlrev_b32_e32 v24, 16, v35
	v_and_b32_e32 v25, 0xffff0000, v35
	v_pk_mul_f32 v[22:23], v[22:23], s[12:13] op_sel_hi:[1,0]
	v_pk_mul_f32 v[24:25], v[24:25], s[12:13] op_sel_hi:[1,0]
	v_cvt_pk_bf16_f32 v22, v22, v23
	v_cvt_pk_bf16_f32 v23, v24, v25
	v_lshlrev_b32_e32 v24, 16, v31
	v_and_b32_e32 v25, 0xffff0000, v31
	v_pk_mul_f32 v[24:25], v[24:25], s[12:13] op_sel_hi:[1,0]
	v_lshlrev_b32_e32 v30, 16, v37
	v_cvt_pk_bf16_f32 v27, v24, v25
	v_lshlrev_b32_e32 v24, 16, v36
	v_and_b32_e32 v25, 0xffff0000, v36
	v_and_b32_e32 v31, 0xffff0000, v37
	v_pk_mul_f32 v[24:25], v[24:25], s[12:13] op_sel_hi:[1,0]
	v_lshlrev_b32_e32 v28, 16, v32
	v_and_b32_e32 v29, 0xffff0000, v32
	v_pk_mul_f32 v[30:31], v[30:31], s[12:13] op_sel_hi:[1,0]
	v_cvt_pk_bf16_f32 v24, v24, v25
	v_pk_mul_f32 v[28:29], v[28:29], s[12:13] op_sel_hi:[1,0]
	v_cvt_pk_bf16_f32 v25, v30, v31
	v_lshlrev_b32_e32 v30, 16, v33
	v_and_b32_e32 v31, 0xffff0000, v33
	s_mov_b64 s[22:23], exec
	v_cvt_pk_bf16_f32 v28, v28, v29
	v_pk_mul_f32 v[52:53], v[30:31], s[12:13] op_sel_hi:[1,0]
